# scan chunk loop: next-chunk input prefetch issued ~0.4 us earlier (start of second prep section); address temps in v250-255; on top of last-barrier elimination
# speedup vs baseline: 1.0067x; 1.0067x over previous
.LBB0_485:
	ds_read_b128 v[8:11], v84 offset:30784
	s_waitcnt vmcnt(4)
	v_lshlrev_b32_e32 v16, 16, v88
	v_and_b32_e32 v17, 0xffff0000, v88
	s_waitcnt vmcnt(2)
	v_lshlrev_b32_e32 v12, 16, v94
	v_and_b32_e32 v13, 0xffff0000, v94
	v_pk_add_f32 v[18:19], v[12:13], v[16:17] neg_lo:[0,1] neg_hi:[0,1]
	ds_read_b128 v[12:15], v84 offset:31296
	s_waitcnt lgkmcnt(1)
	v_pk_fma_f32 v[8:9], v[18:19], v[8:9], v[16:17]
	v_lshlrev_b32_e32 v16, 16, v89
	v_and_b32_e32 v17, 0xffff0000, v89
	v_lshlrev_b32_e32 v18, 16, v95
	v_and_b32_e32 v19, 0xffff0000, v95
	v_pk_add_f32 v[18:19], v[18:19], v[16:17] neg_lo:[0,1] neg_hi:[0,1]
	v_lshlrev_b32_e32 v222, 16, v76
	v_pk_fma_f32 v[10:11], v[18:19], v[10:11], v[16:17]
	v_lshlrev_b32_e32 v16, 16, v86
	v_and_b32_e32 v17, 0xffff0000, v86
	s_waitcnt vmcnt(1)
	v_lshlrev_b32_e32 v18, 16, v98
	v_and_b32_e32 v19, 0xffff0000, v98
	v_pk_add_f32 v[18:19], v[18:19], v[16:17] neg_lo:[0,1] neg_hi:[0,1]
	ds_write_b128 v171, v[8:11] offset:16384
	s_waitcnt lgkmcnt(1)
	v_pk_fma_f32 v[12:13], v[18:19], v[12:13], v[16:17]
	v_lshlrev_b32_e32 v16, 16, v87
	v_and_b32_e32 v17, 0xffff0000, v87
	v_lshlrev_b32_e32 v18, 16, v99
	v_and_b32_e32 v19, 0xffff0000, v99
	v_pk_add_f32 v[18:19], v[18:19], v[16:17] neg_lo:[0,1] neg_hi:[0,1]
	v_and_b32_e32 v223, 0xffff0000, v76
	v_pk_fma_f32 v[14:15], v[18:19], v[14:15], v[16:17]
	ds_write_b128 v171, v[12:15] offset:20480
	ds_write_b128 v164, v[4:7]
	ds_read_b128 v[12:15], v84 offset:31040
	ds_write_b128 v164, v[0:3] offset:16
	s_waitcnt lgkmcnt(0)
	s_barrier
	ds_read_b128 v[16:19], v196 offset:38464
	ds_read_b128 v[20:23], v197 offset:61248
	ds_read_b128 v[116:119], v196 offset:38528
	ds_read_b128 v[210:213], v197 offset:61312
	ds_read_b128 v[214:217], v196 offset:38592
	s_waitcnt lgkmcnt(3)
	v_mfma_f32_16x16x32_bf16 v[16:19], v[16:19], v[20:23], 0
	ds_read_b128 v[20:23], v197 offset:61376
	ds_read_b128 v[218:221], v196 offset:38656
	v_lshlrev_b32_e32 v224, 16, v96
	v_and_b32_e32 v225, 0xffff0000, v96
	s_waitcnt lgkmcnt(3)
	v_mfma_f32_16x16x32_bf16 v[16:19], v[116:119], v[210:213], v[16:19]
	ds_read_b128 v[116:119], v195 offset:33856
	ds_read_b128 v[210:213], v197 offset:61440
	s_waitcnt lgkmcnt(3)
	v_mfma_f32_16x16x32_bf16 v[16:19], v[214:217], v[20:23], v[16:19]
	ds_read_b128 v[20:23], v167 offset:42816
	ds_read_b128 v[214:217], v195 offset:33920
	s_waitcnt lgkmcnt(2)
	v_mfma_f32_16x16x32_bf16 v[16:19], v[218:221], v[210:213], v[16:19]
	ds_read_b128 v[210:213], v167 offset:42880
	v_pk_add_f32 v[218:219], v[224:225], v[222:223] neg_lo:[0,1] neg_hi:[0,1]
	s_waitcnt lgkmcnt(2)
	v_mfma_f32_16x16x32_bf16 v[20:23], v[116:119], v[20:23], 0
	v_fma_f32 v12, v218, v12, v222
	v_fma_f32 v13, v219, v13, v223
	ds_read_b128 v[116:119], v195 offset:36160
	ds_read_b128 v[218:221], v167 offset:52032
	s_waitcnt lgkmcnt(2)
	v_mfma_f32_16x16x32_bf16 v[20:23], v[214:217], v[210:213], v[20:23]
	ds_read_b128 v[210:213], v195 offset:36224
	ds_read_b128 v[214:217], v167 offset:52096
	s_waitcnt lgkmcnt(2)
	v_mfma_f32_16x16x32_bf16 v[116:119], v[116:119], v[218:221], 0
	s_nop 3
	v_add_f32_e32 v20, v207, v20
	v_mul_f32_e32 v20, 0xbfb8aa3b, v20
	v_exp_f32_e32 v20, v20
	s_waitcnt lgkmcnt(0)
	v_mfma_f32_16x16x32_bf16 v[116:119], v[210:213], v[214:217], v[116:119]
	v_add_f32_e32 v21, v207, v21
	v_mul_f32_e32 v21, 0xbfb8aa3b, v21
	v_add_f32_e32 v20, 1.0, v20
	v_div_scale_f32 v40, s[0:1], v20, v20, 1.0
	v_rcp_f32_e32 v209, v40
	s_nop 2
	v_add_f32_e32 v116, v208, v116
	v_mul_f32_e32 v116, 0xbfb8aa3b, v116
	v_exp_f32_e32 v116, v116
	v_fma_f32 v210, -v40, v209, 1.0
	v_fmac_f32_e32 v209, v210, v209
	v_div_scale_f32 v210, vcc, 1.0, v20, 1.0
	v_mul_f32_e32 v211, v210, v209
	v_fma_f32 v212, -v40, v211, v210
	v_fmac_f32_e32 v211, v212, v209
	v_fma_f32 v40, -v40, v211, v210
	v_div_fmas_f32 v40, v40, v209, v211
	v_div_fixup_f32 v20, v40, v20, 1.0
	v_add_f32_e32 v40, 1.0, v116
	v_div_scale_f32 v116, s[0:1], v40, v40, 1.0
	v_rcp_f32_e32 v209, v116
	v_exp_f32_e32 v21, v21
	v_add_f32_e32 v117, v208, v117
	v_mul_f32_e32 v117, 0xbfb8aa3b, v117
	v_fma_f32 v210, -v116, v209, 1.0
	v_fmac_f32_e32 v209, v210, v209
	v_div_scale_f32 v210, vcc, 1.0, v40, 1.0
	v_mul_f32_e32 v211, v210, v209
	v_fma_f32 v212, -v116, v211, v210
	v_fmac_f32_e32 v211, v212, v209
	v_add_f32_e32 v21, 1.0, v21
	v_fma_f32 v116, -v116, v211, v210
	v_div_scale_f32 v210, s[0:1], v21, v21, 1.0
	v_rcp_f32_e32 v212, v210
	v_div_fmas_f32 v116, v116, v209, v211
	v_exp_f32_e32 v117, v117
	v_mul_f32_e32 v20, 0xbf1b4598, v20
	v_fma_f32 v209, -v210, v212, 1.0
	v_fmac_f32_e32 v212, v209, v212
	v_div_scale_f32 v209, vcc, 1.0, v21, 1.0
	v_mul_f32_e32 v211, v209, v212
	v_fma_f32 v213, -v210, v211, v209
	v_fmac_f32_e32 v211, v213, v212
	v_fma_f32 v209, -v210, v211, v209
	v_div_fmas_f32 v209, v209, v212, v211
	v_div_fixup_f32 v21, v209, v21, 1.0
	v_add_f32_e32 v117, 1.0, v117
	v_mul_f32_e32 v21, 0xbf1b4598, v21
	v_div_scale_f32 v209, s[0:1], v117, v117, 1.0
	v_mul_f32_e32 v20, 0x3fb8aa3b, v20
	v_mul_f32_e32 v21, 0x3fb8aa3b, v21
	v_rcp_f32_e32 v210, v209
	v_exp_f32_e32 v20, v20
	v_exp_f32_e32 v21, v21
	v_div_fixup_f32 v40, v116, v40, 1.0
	v_bfe_u32 v116, v16, 16, 1
	v_add3_u32 v16, v16, v116, s91
	ds_write_b16_d16_hi v199, v16 offset:28736
	ds_write2st64_b32 v198, v20, v21 offset1:1
	v_fma_f32 v16, -v209, v210, 1.0
	v_fmac_f32_e32 v210, v16, v210
	v_div_scale_f32 v16, vcc, 1.0, v117, 1.0
	v_mul_f32_e32 v20, v16, v210
	v_fma_f32 v21, -v209, v20, v16
	v_fmac_f32_e32 v20, v21, v210
	v_add_f32_e32 v21, v207, v22
	v_mul_f32_e32 v21, 0xbfb8aa3b, v21
	v_exp_f32_e32 v21, v21
	v_fma_f32 v16, -v209, v20, v16
	v_div_fmas_f32 v16, v16, v210, v20
	v_div_fixup_f32 v16, v16, v117, 1.0
	ds_write2st64_b32 v198, v40, v16 offset0:96 offset1:97
	v_add_f32_e32 v16, 1.0, v21
	v_div_scale_f32 v20, s[0:1], v16, v16, 1.0
	v_rcp_f32_e32 v21, v20
	v_bfe_u32 v22, v17, 16, 1
	v_add3_u32 v17, v17, v22, s91
	ds_write_b16_d16_hi v199, v17 offset:28864
	v_fma_f32 v17, -v20, v21, 1.0
	v_fmac_f32_e32 v21, v17, v21
	v_div_scale_f32 v17, vcc, 1.0, v16, 1.0
	v_mul_f32_e32 v22, v17, v21
	v_fma_f32 v40, -v20, v22, v17
	v_fmac_f32_e32 v22, v40, v21
	v_fma_f32 v17, -v20, v22, v17
	v_add_f32_e32 v20, v208, v118
	v_mul_f32_e32 v20, 0xbfb8aa3b, v20
	v_exp_f32_e32 v20, v20
	v_div_fmas_f32 v17, v17, v21, v22
	v_div_fixup_f32 v16, v17, v16, 1.0
	v_add_f32_e32 v23, v207, v23
	v_add_f32_e32 v17, 1.0, v20
	v_div_scale_f32 v20, s[0:1], v17, v17, 1.0
	v_rcp_f32_e32 v21, v20
	v_mul_f32_e32 v23, 0xbfb8aa3b, v23
	v_exp_f32_e32 v23, v23
	v_mul_f32_e32 v16, 0xbf1b4598, v16
	v_fma_f32 v22, -v20, v21, 1.0
	v_fmac_f32_e32 v21, v22, v21
	v_div_scale_f32 v22, vcc, 1.0, v17, 1.0
	v_mul_f32_e32 v40, v22, v21
	v_fma_f32 v116, -v20, v40, v22
	v_fmac_f32_e32 v40, v116, v21
	v_fma_f32 v20, -v20, v40, v22
	v_add_f32_e32 v22, 1.0, v23
	v_div_scale_f32 v23, s[0:1], v22, v22, 1.0
	v_rcp_f32_e32 v116, v23
	v_div_fmas_f32 v20, v20, v21, v40
	v_mul_f32_e32 v16, 0x3fb8aa3b, v16
	v_exp_f32_e32 v16, v16
	v_fma_f32 v21, -v23, v116, 1.0
	v_fmac_f32_e32 v116, v21, v116
	v_div_scale_f32 v21, vcc, 1.0, v22, 1.0
	v_mul_f32_e32 v40, v21, v116
	v_fma_f32 v117, -v23, v40, v21
	v_fmac_f32_e32 v40, v117, v116
	v_fma_f32 v21, -v23, v40, v21
	v_div_fmas_f32 v21, v21, v116, v40
	v_div_fixup_f32 v21, v21, v22, 1.0
	v_add_f32_e32 v22, v208, v119
	v_mul_f32_e32 v22, 0xbfb8aa3b, v22
	v_exp_f32_e32 v22, v22
	v_mul_f32_e32 v21, 0xbf1b4598, v21
	v_mul_f32_e32 v21, 0x3fb8aa3b, v21
	v_exp_f32_e32 v21, v21
	v_add_f32_e32 v22, 1.0, v22
	v_div_scale_f32 v23, s[0:1], v22, v22, 1.0
	v_rcp_f32_e32 v40, v23
	v_div_fixup_f32 v17, v20, v17, 1.0
	v_bfe_u32 v20, v18, 16, 1
	v_add3_u32 v18, v18, v20, s91
	ds_write_b16_d16_hi v199, v18 offset:28992
	ds_write2st64_b32 v198, v16, v21 offset0:2 offset1:3
	v_fma_f32 v16, -v23, v40, 1.0
	v_fmac_f32_e32 v40, v16, v40
	v_div_scale_f32 v16, vcc, 1.0, v22, 1.0
	v_mul_f32_e32 v18, v16, v40
	v_fma_f32 v20, -v23, v18, v16
	v_fmac_f32_e32 v18, v20, v40
	v_fma_f32 v16, -v23, v18, v16
	v_div_fmas_f32 v16, v16, v40, v18
	v_div_fixup_f32 v16, v16, v22, 1.0
	ds_write2st64_b32 v198, v17, v16 offset0:98 offset1:99
	v_bfe_u32 v16, v19, 16, 1
	v_add3_u32 v16, v19, v16, s91
	ds_write_b16_d16_hi v199, v16 offset:29120
	s_waitcnt lgkmcnt(0)
	s_barrier
	ds_read_b128 v[16:19], v205 offset:31552
	v_lshlrev_b32_e32 v218, 16, v77
	v_and_b32_e32 v219, 0xffff0000, v77
	v_lshlrev_b32_e32 v20, 16, v97
	v_and_b32_e32 v21, 0xffff0000, v97
	s_cmpk_gt_u32 s28, 0x7ef
	s_cbranch_scc1 .Lscan_nopf
	s_add_i32 s62, s28, 16
	s_movk_i32 s88, 0x1000
	s_mov_b32 s89, 0xfffff000
	v_mov_b32_e32 v255, 0
	v_add_u32_e32 v254, s62, v136
	v_lshl_add_u64 v[0:1], s[58:59], 0, v[254:255]
	v_mad_u64_u32 v[250:251], s[86:87], v0, s90, v[90:91]
	v_mad_i32_i24 v251, v1, s90, v251
	v_add_co_u32_e64 v2, s[84:85], s88, v250
	v_lshlrev_b64 v[0:1], 9, v[0:1]
	s_nop 0
	v_addc_co_u32_e64 v3, s[84:85], 0, v251, s[84:85]
	v_lshl_add_u64 v[4:5], v[42:43], 0, v[0:1]
	v_add_co_u32_e64 v252, s[84:85], s89, v250
	global_load_dwordx2 v[76:77], v[250:251], off offset:2048
	global_load_dwordx2 v[86:87], v[2:3], off
	s_nop 0
	global_load_dwordx4 v[0:3], v[4:5], off offset:16
	s_nop 0
	global_load_dwordx4 v[4:7], v[4:5], off
	v_addc_co_u32_e64 v253, s[84:85], -1, v251, s[84:85]
	global_load_dwordx2 v[88:89], v[250:251], off
	global_load_dwordx2 v[94:95], v[252:253], off offset:-2048
	global_load_dwordx2 v[96:97], v[250:251], off offset:-4096
	global_load_dwordx2 v[98:99], v[250:251], off offset:-2048
.Lscan_nopf:
	v_pk_add_f32 v[20:21], v[20:21], v[218:219] neg_lo:[0,1] neg_hi:[0,1]
	s_waitcnt lgkmcnt(0)
	v_pk_mul_f32 v[116:117], v[12:13], v[16:17]
	v_pk_fma_f32 v[22:23], v[20:21], v[14:15], v[218:219]
	v_pk_mul_f32 v[14:15], v[116:117], v[116:117]
	v_pk_mul_f32 v[118:119], v[22:23], v[18:19]
	v_add_f32_e32 v14, v14, v15
	v_pk_mul_f32 v[16:17], v[118:119], v[118:119]
	s_mov_b32 s0, 0xf800000
	v_add_f32_e32 v14, v14, v16
	v_add_f32_e32 v14, v14, v17
	s_nop 1
	v_add_f32_dpp v14, v14, v14 row_ror:8 row_mask:0xf bank_mask:0xf bound_ctrl:1
	s_nop 1
	v_add_f32_dpp v14, v14, v14 row_ror:4 row_mask:0xf bank_mask:0xf bound_ctrl:1
	s_nop 1
	v_add_f32_dpp v14, v14, v14 row_ror:2 row_mask:0xf bank_mask:0xf bound_ctrl:1
	s_nop 1
	v_add_f32_dpp v14, v14, v14 row_ror:1 row_mask:0xf bank_mask:0xf bound_ctrl:1
	v_mul_f32_e32 v15, 0x4f800000, v14
	v_cmp_gt_f32_e32 vcc, s0, v14
	s_nop 1
	v_cndmask_b32_e32 v14, v14, v15, vcc
	v_sqrt_f32_e32 v15, v14
	s_nop 0
	v_add_u32_e32 v16, -1, v15
	v_fma_f32 v17, -v16, v15, v14
	v_cmp_ge_f32_e64 s[0:1], 0, v17
	v_add_u32_e32 v17, 1, v15
	s_nop 0
	v_cndmask_b32_e64 v16, v15, v16, s[0:1]
	v_fma_f32 v15, -v17, v15, v14
	v_cmp_lt_f32_e64 s[0:1], 0, v15
	s_nop 1
	v_cndmask_b32_e64 v15, v16, v17, s[0:1]
	v_mul_f32_e32 v16, 0x37800000, v15
	v_cndmask_b32_e32 v15, v15, v16, vcc
	v_cmp_class_f32_e32 vcc, v14, v201
	s_nop 1
	v_cndmask_b32_e32 v14, v15, v14, vcc
	v_max_f32_e32 v40, 0x2b8cbccc, v14
	v_div_scale_f32 v209, s[0:1], v40, v40, 1.0
	v_rcp_f32_e32 v210, v209
	ds_read_b128 v[14:17], v171 offset:24576
	ds_read_b128 v[18:21], v205 offset:32064
	v_fma_f32 v211, -v209, v210, 1.0
	v_fmac_f32_e32 v210, v211, v210
	v_div_scale_f32 v211, vcc, 1.0, v40, 1.0
	v_mul_f32_e32 v212, v211, v210
	v_fma_f32 v213, -v209, v212, v211
	v_fmac_f32_e32 v212, v213, v210
	v_fma_f32 v209, -v209, v212, v211
	v_div_fmas_f32 v209, v209, v210, v212
	v_div_fixup_f32 v40, v209, v40, 1.0
	v_pk_mul_f32 v[210:211], v[116:117], v[40:41] op_sel_hi:[1,0]
	v_pk_mul_f32 v[212:213], v[118:119], v[40:41] op_sel_hi:[1,0]
	v_xor_b32_e32 v117, 0x80000000, v211
	v_xor_b32_e32 v116, 0x80000000, v210
	v_xor_b32_e32 v119, 0x80000000, v213
	v_xor_b32_e32 v118, 0x80000000, v212
	ds_write_b128 v171, v[116:119] offset:8192
	ds_read_b64 v[116:117], v205 offset:31808
	s_waitcnt lgkmcnt(3)
	v_pk_mul_f32 v[118:119], v[14:15], v[210:211]
	v_pk_add_f32 v[14:15], v[14:15], -1.0 op_sel_hi:[1,0]
	ds_write_b64 v171, v[118:119] offset:12288
	s_waitcnt lgkmcnt(1)
	v_pk_fma_f32 v[14:15], v[14:15], v[116:117], 1.0 op_sel_hi:[1,1,0]
	s_nop 0
	v_pk_mul_f32 v[12:13], v[12:13], v[14:15]
	ds_write_b64 v171, v[12:13] offset:4096
	ds_read_b64 v[14:15], v205 offset:31816
	v_pk_mul_f32 v[116:117], v[16:17], v[212:213]
	v_pk_add_f32 v[16:17], v[16:17], -1.0 op_sel_hi:[1,0]
	v_pk_mul_f32 v[8:9], v[8:9], v[12:13]
	ds_write_b64 v171, v[116:117] offset:12296
	s_waitcnt lgkmcnt(1)
	v_pk_fma_f32 v[14:15], v[16:17], v[14:15], 1.0 op_sel_hi:[1,1,0]
	v_mul_f32_e32 v12, v9, v19
	v_pk_mul_f32 v[14:15], v[22:23], v[14:15]
	v_fmac_f32_e32 v12, v8, v18
	v_pk_mul_f32 v[8:9], v[10:11], v[14:15]
	ds_write_b64 v171, v[14:15] offset:4104
	v_fmac_f32_e32 v12, v8, v20
	v_fmac_f32_e32 v12, v9, v21
	s_nop 1
	v_add_f32_dpp v8, v12, v12 row_ror:8 row_mask:0xf bank_mask:0xf bound_ctrl:1
	s_nop 1
	v_add_f32_dpp v8, v8, v8 row_ror:4 row_mask:0xf bank_mask:0xf bound_ctrl:1
	s_nop 1
	v_add_f32_dpp v8, v8, v8 row_ror:2 row_mask:0xf bank_mask:0xf bound_ctrl:1
	s_nop 1
	v_mov_b32_dpp v9, v8 row_ror:1 row_mask:0xf bank_mask:0xf bound_ctrl:1
	s_and_saveexec_b64 s[0:1], s[24:25]
	v_add_f32_e32 v8, v8, v9
	ds_write_b32 v163, v8 offset:28672
	s_or_b64 exec, exec, s[0:1]
	s_add_i32 s62, s28, 16
	s_cmpk_gt_u32 s28, 0x7ef
	s_cselect_b64 s[0:1], -1, 0
	s_and_b64 vcc, exec, s[0:1]
	s_cbranch_vccnz .LBB0_489

	.amdhsa_kernel _Z11mega_kernel6Params
		.amdhsa_group_segment_fixed_size 79892
		.amdhsa_private_segment_fixed_size 0
		.amdhsa_kernarg_size 696
		.amdhsa_user_sgpr_count 2
		.amdhsa_user_sgpr_dispatch_ptr 0
		.amdhsa_user_sgpr_queue_ptr 0
		.amdhsa_user_sgpr_kernarg_segment_ptr 1
		.amdhsa_user_sgpr_dispatch_id 0
		.amdhsa_user_sgpr_kernarg_preload_length 0
		.amdhsa_user_sgpr_kernarg_preload_offset 0
		.amdhsa_user_sgpr_private_segment_size 0
		.amdhsa_uses_dynamic_stack 0
		.amdhsa_enable_private_segment 0
		.amdhsa_system_sgpr_workgroup_id_x 1
		.amdhsa_system_sgpr_workgroup_id_y 0
		.amdhsa_system_sgpr_workgroup_id_z 0
		.amdhsa_system_sgpr_workgroup_info 0
		.amdhsa_system_vgpr_workitem_id 2
		.amdhsa_next_free_vgpr 256
		.amdhsa_next_free_sgpr 98
		.amdhsa_accum_offset 256
		.amdhsa_reserve_vcc 1
		.amdhsa_float_round_mode_32 0
		.amdhsa_float_round_mode_16_64 0
		.amdhsa_float_denorm_mode_32 3
		.amdhsa_float_denorm_mode_16_64 3
		.amdhsa_dx10_clamp 1
		.amdhsa_ieee_mode 1
		.amdhsa_fp16_overflow 0
		.amdhsa_tg_split 0
		.amdhsa_exception_fp_ieee_invalid_op 0
		.amdhsa_exception_fp_denorm_src 0
		.amdhsa_exception_fp_ieee_div_zero 0
		.amdhsa_exception_fp_ieee_overflow 0
		.amdhsa_exception_fp_ieee_underflow 0
		.amdhsa_exception_fp_ieee_inexact 0
		.amdhsa_exception_int_div_zero 0
	.end_amdhsa_kernel

amdhsa.kernels:
  - .agpr_count:     0
    .args:
      - .offset:         0
        .size:           440
        .value_kind:     by_value
      - .offset:         440
        .size:           4
        .value_kind:     hidden_block_count_x
      - .offset:         444
        .size:           4
        .value_kind:     hidden_block_count_y
      - .offset:         448
        .size:           4
        .value_kind:     hidden_block_count_z
      - .offset:         452
        .size:           2
        .value_kind:     hidden_group_size_x
      - .offset:         454
        .size:           2
        .value_kind:     hidden_group_size_y
      - .offset:         456
        .size:           2
        .value_kind:     hidden_group_size_z
      - .offset:         458
        .size:           2
        .value_kind:     hidden_remainder_x
      - .offset:         460
        .size:           2
        .value_kind:     hidden_remainder_y
      - .offset:         462
        .size:           2
        .value_kind:     hidden_remainder_z
      - .offset:         480
        .size:           8
        .value_kind:     hidden_global_offset_x
      - .offset:         488
        .size:           8
        .value_kind:     hidden_global_offset_y
      - .offset:         496
        .size:           8
        .value_kind:     hidden_global_offset_z
      - .offset:         504
        .size:           2
        .value_kind:     hidden_grid_dims
      - .offset:         528
        .size:           8
        .value_kind:     hidden_multigrid_sync_arg
    .group_segment_fixed_size: 79892
    .kernarg_segment_align: 8
    .kernarg_segment_size: 696
    .language:       OpenCL C
    .language_version:
      - 2
      - 0
    .max_flat_workgroup_size: 256
    .name:           _Z11mega_kernel6Params
    .private_segment_fixed_size: 0
    .sgpr_count:     104
    .sgpr_spill_count: 225
    .symbol:         _Z11mega_kernel6Params.kd
    .uniform_work_group_size: 1
    .uses_dynamic_stack: false
    .vgpr_count:     256
    .vgpr_spill_count: 0
    .wavefront_size: 64
